# attention item setup: rel-bias LDS table loaded once per layer (items 0..4 share the head), sink value via scalar load instead of a vmcnt(0) round trip
# speedup vs baseline: 1.0125x; 1.0125x over previous
; DI void attn_phase(const Params& P, LAS unsigned char* lds, int layer) {
;     ...
;         if (mixB) { for (int i = tid; i < 257; i += NTHR) bt[i] = relb[hk * 257 + i] * LOG2E; }
.LBB0_1330:
	v_cndmask_b32_e64 v0, 0, 1, s[18:19]
	v_cmp_ne_u32_e64 s[44:45], 1, v0
	s_andn2_b64 vcc, exec, s[18:19]
	s_mov_b64 s[18:19], -1
	s_cbranch_vccnz .LBB0_1342
	s_cmp_lg_u32 s7, 0
	s_cbranch_scc1 .LBB0_1341
	s_and_saveexec_b64 s[18:19], s[38:39]
	s_cbranch_execz .LBB0_1341
	s_mov_b64 s[24:25], -1
	v_mov_b32_e32 v0, v164
	v_mov_b32_e32 v1, v198
	s_and_saveexec_b64 s[20:21], s[40:41]
	s_cbranch_execz .LBB0_1338
	s_mul_i32 s0, s50, 0x101
	s_mov_b32 s1, s0
	s_mov_b64 s[24:25], 0
	v_mov_b32_e32 v2, v196
	v_mov_b32_e32 v3, v199
	v_mov_b64_e32 v[0:1], v[164:165]

; DI void attn_phase(const Params& P, LAS unsigned char* lds, int layer) {
;     ...
;         const float sinkv = mixB ? -1e30f : sinks[hq] * LOG2E;
.LBB0_1342:
	s_mov_b32 s48, s96
	s_andn2_b64 vcc, exec, s[18:19]
	v_mov_b32_e32 v175, 0xf149f2ca
	s_cbranch_vccnz .LBB0_1344
	s_ashr_i32 s17, s16, 31
	s_lshl_b64 s[0:1], s[16:17], 2
	v_readlane_b32 s2, v246, 41
	s_add_u32 s0, s2, s0
	v_readlane_b32 s2, v246, 42
	s_addc_u32 s1, s2, s1
	s_load_dword s2, s[0:1], 0x0
	s_waitcnt lgkmcnt(0)
	v_mov_b32_e32 v0, s2
	v_mul_f32_e32 v175, 0x3fb8aa3b, v0
